# dilated loop: next-chunk K/V addresses as SGPR base + 32-bit offsets (no 64-bit VALU address math), on top of the previous dilated-loop changes
# speedup vs baseline: 1.0037x; 1.0037x over previous
.LBB0_676:
	s_waitcnt lgkmcnt(9)
	v_add_u32_e32 v0, s2, v199
	v_mul_lo_u32 v0, v0, s3
	v_add_u32_e32 v0, s14, v0
	s_waitcnt lgkmcnt(8)
	v_add_u32_e32 v0, s10, v0
	s_lshl_b32 s0, s3, 14
	v_lshl_or_b32 v2, v0, 11, v225
	global_load_dwordx4 v[160:163], v2, s[40:41]
	global_load_dwordx4 v[164:167], v2, s[42:43]
	v_add_u32_e32 v3, s0, v2
	global_load_dwordx4 v[168:171], v3, s[40:41]
	global_load_dwordx4 v[172:175], v3, s[42:43]
	v_add_u32_e32 v4, s0, v3
	global_load_dwordx4 v[176:179], v4, s[40:41]
	global_load_dwordx4 v[180:183], v4, s[42:43]
	v_add_u32_e32 v5, s0, v4
	global_load_dwordx4 v[184:187], v5, s[40:41]
	global_load_dwordx4 v[188:191], v5, s[42:43]
